# P1 K-loop head aligned to 64 bytes (.p2align 6)
# speedup vs baseline: 1.0018x; 1.0018x over previous
; #define PG8_LAS __attribute__((address_space(3)))
; #define PG8_STAGE(bufoff, gbase, voff) do { _Pragma("unroll") for (int _i = 0; _i < 2; ++_i) \
;         __builtin_amdgcn_global_load_lds((const unsigned*)((const char*)(gbase) + (voff)[_i]), (PG8_LAS unsigned*)(lds + (bufoff) + ldsw + _i * 8192), 16, 0, 0); } while (0)
; #define PG8_WAIT_V(n) asm volatile("s_waitcnt vmcnt(" #n ")" ::: "memory")
; #define PG8_WAIT_L(n) asm volatile("s_waitcnt lgkmcnt(" #n ")" ::: "memory")
; template <class Epi, class Sched, bool ALIGN_EPI = false, bool SP2 = false, bool RS = false, bool BPRE = false>
; __device__ __forceinline__ void gemm_phase(PG8_LAS unsigned char* lds, const Gemm g, const Sched& S, const Epi& E, const float* rs_ss = nullptr, PG8_LAS float* rs_tab = nullptr) {
;     ...
;         const char* nA = has_next ? (const char*)g.A + (size_t)nxt.pm * tstep : cA; const char* nB = has_next ? (const char*)g.Bt + (size_t)nxt.pn * tstep : cB;
;         for (int t = 0; t < nt; t += 2) {
;             const bool last = (t == nt - 2);
;             if constexpr (RS) { if (t == 16 || t == 32) { const PG8_LAS float* tp = rs_tab + (ui & 1) * 768 + (t == 32 ? 256 : 0);
;                 _Pragma("unroll") for (int a = 0; a < 2; ++a) _Pragma("unroll") for (int m = 0; m < 4; ++m) { const float f = tp[a * HALF + wr * 64 + m * 16 + fr];
;                     _Pragma("unroll") for (int b = 0; b < 2; ++b) _Pragma("unroll") for (int n = 0; n < 2; ++n) acc[a][b][m][n] = acc[a][b][m][n] * f; } } }
;             const char* a1 = cA + (size_t)(t + 1) * kstep;
;             const char* a2 = last ? nA : cA + (size_t)(t + 2) * kstep; const char* b2 = last ? nB : cB + (size_t)(t + 2) * kstep;
;             const char* a3 = a2 + kstep; const char* b3 = b2 + kstep;
;             if (last && has_next) S.a_ready(nxt);
;             if constexpr (SP2) {
;             PG8_LDB(B0, 0, 0); PG8_LDB(B1, 0, 1); PG8_SCHED; PG8_LDA(At, 0, 0); PG8_STAGE(PG8_SA(1, 1), a1 + hstep, voffA);
;             PG8_WAIT_V(8); PG8_WAIT_L(0); PG8_BAR; PG8_MMA(0, 0, At, B0); PG8_MMA(0, 1, At, B1); PG8_BAR; PG8_SCHED;
;             PG8_LDA(At, 0, 1); PG8_STAGE(PG8_SB(0, 0), b2, voffB); PG8_STAGE(PG8_SB(0, 1), b2 + hstep, voffB); PG8_STAGE(PG8_SA(0, 0), a2, voffA);
;             PG8_WAIT_V(8); PG8_WAIT_L(0); PG8_BAR; PG8_MMA(1, 0, At, B0); PG8_MMA(1, 1, At, B1); PG8_BAR; PG8_SCHED;
.LBB0_195:
	s_ashr_i32 s19, s18, 31
	s_lshl_b64 s[20:21], s[18:19], 20
	s_add_u32 s20, s30, s20
	s_addc_u32 s21, s31, s21
	s_and_b64 s[44:45], s[6:7], exec
	s_cselect_b32 s5, s21, s57
	s_cselect_b32 s19, s20, s56
	s_ashr_i32 s17, s16, 31
	s_lshl_b64 s[44:45], s[16:17], 20
	s_add_u32 s44, s24, s44
	s_addc_u32 s45, s25, s45
	s_and_b64 s[60:61], s[6:7], exec
	s_cselect_b32 s17, s45, s59
	s_cselect_b32 s47, s44, s58
	s_add_u32 s56, s56, 0x84000
	s_addc_u32 s57, s57, 0
	s_add_u32 s87, s58, 0x8000
	s_addc_u32 s88, s59, 0
	s_mov_b32 s89, -2
	s_waitcnt lgkmcnt(0)
	ds_read_b128 v[130:133], v161
	ds_read_b128 v[134:137], v161 offset:1024
	ds_read_b128 v[152:155], v161 offset:2048
	ds_read_b128 v[156:159], v161 offset:3072
	ds_read_b128 v[166:169], v162
	ds_read_b128 v[170:173], v162 offset:1024
	ds_read_b128 v[174:177], v162 offset:2048
	ds_read_b128 v[182:185], v162 offset:3072
	s_add_u32 s58, s56, 0xfff84000
	s_addc_u32 s59, s57, -1
	s_cmp_eq_u32 s89, 28
	s_cselect_b32 s70, s19, s58
	s_cselect_b32 s71, s5, s59
	s_cselect_b32 s60, s47, s87
	s_cselect_b32 s61, s17, s88
	s_add_u32 s58, s70, 0x4000
	s_addc_u32 s59, s71, 0
	v_lshl_add_u64 v[178:179], s[56:57], 0, v[138:139]
	s_add_i32 m0, s72, 0xc000
	ds_read_b128 v[186:189], v163
	ds_read_b128 v[190:193], v163 offset:1024
	ds_read_b128 v[194:197], v163 offset:2048
	ds_read_b128 v[198:201], v163 offset:3072
	ds_read_b128 v[202:205], v163 offset:4096
	ds_read_b128 v[206:209], v163 offset:5120
	ds_read_b128 v[210:213], v163 offset:6144
	ds_read_b128 v[214:217], v163 offset:7168
	global_load_lds_dwordx4 v[178:179], off
	v_lshl_add_u64 v[178:179], s[56:57], 0, v[146:147]
	s_add_i32 m0, s72, 0xe000
	s_nop 0
	global_load_lds_dwordx4 v[178:179], off
	s_waitcnt vmcnt(8)
	s_waitcnt lgkmcnt(0)
	s_barrier
	s_setprio 1
	s_waitcnt lgkmcnt(0)
	v_mfma_f32_16x16x32_bf16 v[126:129], v[130:133], v[186:189], 0
	v_mfma_f32_16x16x32_bf16 v[122:125], v[152:155], v[186:189], 0
	v_mfma_f32_16x16x32_bf16 v[110:113], v[130:133], v[194:197], 0
	v_mfma_f32_16x16x32_bf16 v[106:109], v[152:155], v[194:197], 0
	v_mfma_f32_16x16x32_bf16 v[94:97], v[130:133], v[202:205], 0
	v_mfma_f32_16x16x32_bf16 v[90:93], v[152:155], v[202:205], 0
	v_mfma_f32_16x16x32_bf16 v[78:81], v[130:133], v[210:213], 0
	v_mfma_f32_16x16x32_bf16 v[74:77], v[152:155], v[210:213], 0
	v_mfma_f32_16x16x32_bf16 v[126:129], v[134:137], v[190:193], v[126:129]
	v_mfma_f32_16x16x32_bf16 v[122:125], v[156:159], v[190:193], v[122:125]
	v_mfma_f32_16x16x32_bf16 v[110:113], v[134:137], v[198:201], v[110:113]
	v_mfma_f32_16x16x32_bf16 v[106:109], v[156:159], v[198:201], v[106:109]
	v_mfma_f32_16x16x32_bf16 v[94:97], v[134:137], v[206:209], v[94:97]
	v_mfma_f32_16x16x32_bf16 v[90:93], v[156:159], v[206:209], v[90:93]
	v_mfma_f32_16x16x32_bf16 v[78:81], v[134:137], v[214:217], v[78:81]
	v_mfma_f32_16x16x32_bf16 v[74:77], v[156:159], v[214:217], v[74:77]
	s_setprio 0
	s_setprio 1
	v_mfma_f32_16x16x32_bf16 v[118:121], v[166:169], v[186:189], 0
	v_mfma_f32_16x16x32_bf16 v[114:117], v[174:177], v[186:189], 0
	v_mfma_f32_16x16x32_bf16 v[102:105], v[166:169], v[194:197], 0
	v_mfma_f32_16x16x32_bf16 v[98:101], v[174:177], v[194:197], 0
	v_mfma_f32_16x16x32_bf16 v[86:89], v[166:169], v[202:205], 0
	v_mfma_f32_16x16x32_bf16 v[82:85], v[174:177], v[202:205], 0
	v_mfma_f32_16x16x32_bf16 v[70:73], v[166:169], v[210:213], 0
	v_mfma_f32_16x16x32_bf16 v[66:69], v[174:177], v[210:213], 0
	v_mfma_f32_16x16x32_bf16 v[118:121], v[170:173], v[190:193], v[118:121]
	v_mfma_f32_16x16x32_bf16 v[114:117], v[182:185], v[190:193], v[114:117]
	v_mfma_f32_16x16x32_bf16 v[102:105], v[170:173], v[198:201], v[102:105]
	v_mfma_f32_16x16x32_bf16 v[98:101], v[182:185], v[198:201], v[98:101]
	v_mfma_f32_16x16x32_bf16 v[86:89], v[170:173], v[206:209], v[86:89]
	v_mfma_f32_16x16x32_bf16 v[82:85], v[182:185], v[206:209], v[82:85]
	v_mfma_f32_16x16x32_bf16 v[70:73], v[170:173], v[214:217], v[70:73]
	v_mfma_f32_16x16x32_bf16 v[66:69], v[182:185], v[214:217], v[66:69]
	s_setprio 0
	s_barrier
	s_add_i32 s90, s83, s15
	v_lshl_add_u64 v[178:179], s[60:61], 0, v[138:139]
	s_mov_b32 m0, s90
	ds_read_b128 v[186:189], v163 offset:16384
	ds_read_b128 v[190:193], v163 offset:17408
	ds_read_b128 v[194:197], v163 offset:18432
	ds_read_b128 v[198:201], v163 offset:19456
	ds_read_b128 v[202:205], v163 offset:20480
	ds_read_b128 v[206:209], v163 offset:21504
	ds_read_b128 v[210:213], v163 offset:22528
	ds_read_b128 v[214:217], v163 offset:23552
	global_load_lds_dwordx4 v[178:179], off
	s_add_i32 m0, s90, 0x2000
	s_add_u32 s90, s60, 0x80000
	v_lshl_add_u64 v[178:179], s[60:61], 0, v[140:141]
	s_addc_u32 s91, s61, 0
	s_add_i32 s92, s86, s15
	global_load_lds_dwordx4 v[178:179], off
	v_lshl_add_u64 v[178:179], s[90:91], 0, v[138:139]
	s_mov_b32 m0, s92
	s_nop 0
	global_load_lds_dwordx4 v[178:179], off
	v_lshl_add_u64 v[178:179], s[90:91], 0, v[140:141]
	s_add_i32 m0, s92, 0x2000
	s_nop 0
	global_load_lds_dwordx4 v[178:179], off
	v_lshl_add_u64 v[178:179], s[70:71], 0, v[138:139]
	s_mov_b32 m0, s72
	s_nop 0
	global_load_lds_dwordx4 v[178:179], off
	v_lshl_add_u64 v[178:179], s[70:71], 0, v[140:141]
	s_mov_b32 m0, s73
	s_nop 0
	global_load_lds_dwordx4 v[178:179], off
	s_waitcnt vmcnt(8)
	s_waitcnt lgkmcnt(0)
	s_barrier
; #define PG8_STAGE(bufoff, gbase, voff) do { _Pragma("unroll") for (int _i = 0; _i < 2; ++_i) \
;         __builtin_amdgcn_global_load_lds((const unsigned*)((const char*)(gbase) + (voff)[_i]), (PG8_LAS unsigned*)(lds + (bufoff) + ldsw + _i * 8192), 16, 0, 0); } while (0)
; #define PG8_LDA(dst, b, h) do { _Pragma("unroll") for (int m = 0; m < 4; ++m) _Pragma("unroll") for (int k = 0; k < 2; ++k) dst[m][k] = *(const PG8_LAS bf16x8*)(lds + PG8_SA(b, h) + aoff + m * 2048 + k * 1024); } while (0)
; #define PG8_LDB(dst, b, h) do { _Pragma("unroll") for (int n = 0; n < 2; ++n) _Pragma("unroll") for (int k = 0; k < 2; ++k) dst[n][k] = *(const PG8_LAS bf16x8*)(lds + PG8_SB(b, h) + boff + n * 2048 + k * 1024); } while (0)
; #define PG8_MMA(ai, bj, At, Bt) do { __builtin_amdgcn_s_setprio(1); _Pragma("unroll") for (int m = 0; m < 4; ++m) _Pragma("unroll") for (int n = 0; n < 2; ++n) _Pragma("unroll") for (int k = 0; k < 2; ++k) \
;         acc[ai][bj][m][n] = __builtin_amdgcn_mfma_f32_16x16x32_bf16(Bt[n][k], At[m][k], acc[ai][bj][m][n], 0, 0, 0); __builtin_amdgcn_s_setprio(0); } while (0)
; #define PG8_WAIT_V(n) asm volatile("s_waitcnt vmcnt(" #n ")" ::: "memory")
; #define PG8_WAIT_L(n) asm volatile("s_waitcnt lgkmcnt(" #n ")" ::: "memory")
; #define PG8_BAR __builtin_amdgcn_s_barrier()
; #define PG8_SCHED __builtin_amdgcn_sched_barrier(0)
; template <class Epi, class Sched, bool ALIGN_EPI = false, bool SP2 = false, bool RS = false, bool BPRE = false>
; __device__ __forceinline__ void gemm_phase(PG8_LAS unsigned char* lds, const Gemm g, const Sched& S, const Epi& E, const float* rs_ss = nullptr, PG8_LAS float* rs_tab = nullptr) {
;     ...
;             PG8_WAIT_V(8); PG8_WAIT_L(0); PG8_BAR; PG8_MMA(1, 0, At, B0); PG8_MMA(1, 1, At, B1); PG8_BAR; PG8_SCHED;
;             PG8_LDB(B0, 1, 0); PG8_LDB(B1, 1, 1); PG8_SCHED; PG8_LDA(At, 1, 0); PG8_STAGE(PG8_SA(0, 1), a2 + hstep, voffA);
;             PG8_WAIT_V(8); PG8_WAIT_L(0); PG8_BAR; PG8_MMA(0, 0, At, B0); PG8_MMA(0, 1, At, B1); PG8_BAR; PG8_SCHED;
;             PG8_LDA(At, 1, 1); PG8_STAGE(PG8_SB(1, 0), b3, voffB); PG8_STAGE(PG8_SB(1, 1), b3 + hstep, voffB); PG8_STAGE(PG8_SA(1, 0), a3, voffA);
;             PG8_WAIT_V(8); PG8_WAIT_L(0); PG8_BAR; PG8_MMA(1, 0, At, B0); PG8_MMA(1, 1, At, B1); PG8_BAR; PG8_SCHED;
	s_setprio 1
	s_waitcnt lgkmcnt(0)
	v_mfma_f32_16x16x32_bf16 v[62:65], v[130:133], v[186:189], 0
	v_mfma_f32_16x16x32_bf16 v[58:61], v[152:155], v[186:189], 0
	v_mfma_f32_16x16x32_bf16 v[46:49], v[130:133], v[194:197], 0
	v_mfma_f32_16x16x32_bf16 v[42:45], v[152:155], v[194:197], 0
	v_mfma_f32_16x16x32_bf16 v[30:33], v[130:133], v[202:205], 0
	v_mfma_f32_16x16x32_bf16 v[26:29], v[152:155], v[202:205], 0
	v_mfma_f32_16x16x32_bf16 v[14:17], v[130:133], v[210:213], 0
	v_mfma_f32_16x16x32_bf16 v[10:13], v[152:155], v[210:213], 0
	v_mfma_f32_16x16x32_bf16 v[62:65], v[134:137], v[190:193], v[62:65]
	v_mfma_f32_16x16x32_bf16 v[58:61], v[156:159], v[190:193], v[58:61]
	v_mfma_f32_16x16x32_bf16 v[46:49], v[134:137], v[198:201], v[46:49]
	v_mfma_f32_16x16x32_bf16 v[42:45], v[156:159], v[198:201], v[42:45]
	v_mfma_f32_16x16x32_bf16 v[30:33], v[134:137], v[206:209], v[30:33]
	v_mfma_f32_16x16x32_bf16 v[26:29], v[156:159], v[206:209], v[26:29]
	v_mfma_f32_16x16x32_bf16 v[14:17], v[134:137], v[214:217], v[14:17]
	v_mfma_f32_16x16x32_bf16 v[10:13], v[156:159], v[214:217], v[10:13]
	s_setprio 0
	s_setprio 1
	v_mfma_f32_16x16x32_bf16 v[54:57], v[166:169], v[186:189], 0
	v_mfma_f32_16x16x32_bf16 v[50:53], v[174:177], v[186:189], 0
	v_mfma_f32_16x16x32_bf16 v[38:41], v[166:169], v[194:197], 0
	v_mfma_f32_16x16x32_bf16 v[34:37], v[174:177], v[194:197], 0
	v_mfma_f32_16x16x32_bf16 v[22:25], v[166:169], v[202:205], 0
	v_mfma_f32_16x16x32_bf16 v[18:21], v[174:177], v[202:205], 0
	v_mfma_f32_16x16x32_bf16 v[6:9], v[166:169], v[210:213], 0
	v_mfma_f32_16x16x32_bf16 v[2:5], v[174:177], v[210:213], 0
	v_mfma_f32_16x16x32_bf16 v[54:57], v[170:173], v[190:193], v[54:57]
	v_mfma_f32_16x16x32_bf16 v[50:53], v[182:185], v[190:193], v[50:53]
	v_mfma_f32_16x16x32_bf16 v[38:41], v[170:173], v[198:201], v[38:41]
	v_mfma_f32_16x16x32_bf16 v[34:37], v[182:185], v[198:201], v[34:37]
	v_mfma_f32_16x16x32_bf16 v[22:25], v[170:173], v[206:209], v[22:25]
	v_mfma_f32_16x16x32_bf16 v[18:21], v[182:185], v[206:209], v[18:21]
	v_mfma_f32_16x16x32_bf16 v[6:9], v[170:173], v[214:217], v[6:9]
	v_mfma_f32_16x16x32_bf16 v[2:5], v[182:185], v[214:217], v[2:5]
	s_setprio 0
	s_barrier
	s_add_i32 s90, 0, 0x18000
	v_add_u32_e32 v143, s90, v160
	s_add_i32 s91, 0, 0x1c000
	ds_read_b128 v[130:133], v143
	ds_read_b128 v[134:137], v143 offset:1024
	ds_read_b128 v[152:155], v143 offset:2048
	ds_read_b128 v[156:159], v143 offset:3072
	v_add_u32_e32 v143, s91, v160
	ds_read_b128 v[166:169], v143
	ds_read_b128 v[170:173], v143 offset:1024
	ds_read_b128 v[174:177], v143 offset:2048
	ds_read_b128 v[182:185], v143 offset:3072
	s_add_u32 s70, s70, 0x80000
	s_addc_u32 s71, s71, 0
	s_mov_b32 m0, s74
	v_lshl_add_u64 v[178:179], s[70:71], 0, v[138:139]
	ds_read_b128 v[186:189], v163 offset:32768
	ds_read_b128 v[190:193], v163 offset:33792
	ds_read_b128 v[194:197], v163 offset:34816
	ds_read_b128 v[198:201], v163 offset:35840
	ds_read_b128 v[202:205], v163 offset:36864
	ds_read_b128 v[206:209], v163 offset:37888
	ds_read_b128 v[210:213], v163 offset:38912
	ds_read_b128 v[214:217], v163 offset:39936
	global_load_lds_dwordx4 v[178:179], off
	v_lshl_add_u64 v[178:179], s[70:71], 0, v[140:141]
	s_mov_b32 m0, s75
	s_nop 0
	global_load_lds_dwordx4 v[178:179], off
	s_waitcnt vmcnt(8)
	s_waitcnt lgkmcnt(0)
	s_barrier
	s_setprio 1
	s_waitcnt lgkmcnt(0)
	v_mfma_f32_16x16x32_bf16 v[126:129], v[130:133], v[186:189], v[126:129]
	v_mfma_f32_16x16x32_bf16 v[122:125], v[152:155], v[186:189], v[122:125]
	v_mfma_f32_16x16x32_bf16 v[110:113], v[130:133], v[194:197], v[110:113]
	v_mfma_f32_16x16x32_bf16 v[106:109], v[152:155], v[194:197], v[106:109]
	v_mfma_f32_16x16x32_bf16 v[94:97], v[130:133], v[202:205], v[94:97]
	v_mfma_f32_16x16x32_bf16 v[90:93], v[152:155], v[202:205], v[90:93]
	v_mfma_f32_16x16x32_bf16 v[78:81], v[130:133], v[210:213], v[78:81]
	v_mfma_f32_16x16x32_bf16 v[74:77], v[152:155], v[210:213], v[74:77]
	v_mfma_f32_16x16x32_bf16 v[126:129], v[134:137], v[190:193], v[126:129]
	v_mfma_f32_16x16x32_bf16 v[122:125], v[156:159], v[190:193], v[122:125]
	v_mfma_f32_16x16x32_bf16 v[110:113], v[134:137], v[198:201], v[110:113]
	v_mfma_f32_16x16x32_bf16 v[106:109], v[156:159], v[198:201], v[106:109]
	v_mfma_f32_16x16x32_bf16 v[94:97], v[134:137], v[206:209], v[94:97]
	v_mfma_f32_16x16x32_bf16 v[90:93], v[156:159], v[206:209], v[90:93]
	v_mfma_f32_16x16x32_bf16 v[78:81], v[134:137], v[214:217], v[78:81]
	v_mfma_f32_16x16x32_bf16 v[74:77], v[156:159], v[214:217], v[74:77]
	s_setprio 0
	s_setprio 1
	v_mfma_f32_16x16x32_bf16 v[118:121], v[166:169], v[186:189], v[118:121]
	v_mfma_f32_16x16x32_bf16 v[114:117], v[174:177], v[186:189], v[114:117]
	v_mfma_f32_16x16x32_bf16 v[102:105], v[166:169], v[194:197], v[102:105]
	v_mfma_f32_16x16x32_bf16 v[98:101], v[174:177], v[194:197], v[98:101]
	v_mfma_f32_16x16x32_bf16 v[86:89], v[166:169], v[202:205], v[86:89]
	v_mfma_f32_16x16x32_bf16 v[82:85], v[174:177], v[202:205], v[82:85]
	v_mfma_f32_16x16x32_bf16 v[70:73], v[166:169], v[210:213], v[70:73]
	v_mfma_f32_16x16x32_bf16 v[66:69], v[174:177], v[210:213], v[66:69]
	v_mfma_f32_16x16x32_bf16 v[118:121], v[170:173], v[190:193], v[118:121]
	v_mfma_f32_16x16x32_bf16 v[114:117], v[182:185], v[190:193], v[114:117]
	v_mfma_f32_16x16x32_bf16 v[102:105], v[170:173], v[198:201], v[102:105]
	v_mfma_f32_16x16x32_bf16 v[98:101], v[182:185], v[198:201], v[98:101]
	v_mfma_f32_16x16x32_bf16 v[86:89], v[170:173], v[206:209], v[86:89]
	v_mfma_f32_16x16x32_bf16 v[82:85], v[182:185], v[206:209], v[82:85]
	v_mfma_f32_16x16x32_bf16 v[70:73], v[170:173], v[214:217], v[70:73]
	v_mfma_f32_16x16x32_bf16 v[66:69], v[182:185], v[214:217], v[66:69]
	s_setprio 0
	s_barrier
; #define PG8_STAGE(bufoff, gbase, voff) do { _Pragma("unroll") for (int _i = 0; _i < 2; ++_i) \
;         __builtin_amdgcn_global_load_lds((const unsigned*)((const char*)(gbase) + (voff)[_i]), (PG8_LAS unsigned*)(lds + (bufoff) + ldsw + _i * 8192), 16, 0, 0); } while (0)
; #define PG8_LDA(dst, b, h) do { _Pragma("unroll") for (int m = 0; m < 4; ++m) _Pragma("unroll") for (int k = 0; k < 2; ++k) dst[m][k] = *(const PG8_LAS bf16x8*)(lds + PG8_SA(b, h) + aoff + m * 2048 + k * 1024); } while (0)
; #define PG8_MMA(ai, bj, At, Bt) do { __builtin_amdgcn_s_setprio(1); _Pragma("unroll") for (int m = 0; m < 4; ++m) _Pragma("unroll") for (int n = 0; n < 2; ++n) _Pragma("unroll") for (int k = 0; k < 2; ++k) \
;         acc[ai][bj][m][n] = __builtin_amdgcn_mfma_f32_16x16x32_bf16(Bt[n][k], At[m][k], acc[ai][bj][m][n], 0, 0, 0); __builtin_amdgcn_s_setprio(0); } while (0)
; #define PG8_WAIT_V(n) asm volatile("s_waitcnt vmcnt(" #n ")" ::: "memory")
; #define PG8_WAIT_L(n) asm volatile("s_waitcnt lgkmcnt(" #n ")" ::: "memory")
; #define PG8_BAR __builtin_amdgcn_s_barrier()
; #define PG8_SCHED __builtin_amdgcn_sched_barrier(0)
; template <class Epi, class Sched, bool ALIGN_EPI = false, bool SP2 = false, bool RS = false, bool BPRE = false>
; __device__ __forceinline__ void gemm_phase(PG8_LAS unsigned char* lds, const Gemm g, const Sched& S, const Epi& E, const float* rs_ss = nullptr, PG8_LAS float* rs_tab = nullptr) {
;     ...
;         for (int t = 0; t < nt; t += 2) {
;     ...
;             PG8_LDA(At, 1, 1); PG8_STAGE(PG8_SB(1, 0), b3, voffB); PG8_STAGE(PG8_SB(1, 1), b3 + hstep, voffB); PG8_STAGE(PG8_SA(1, 0), a3, voffA);
;             PG8_WAIT_V(8); PG8_WAIT_L(0); PG8_BAR; PG8_MMA(1, 0, At, B0); PG8_MMA(1, 1, At, B1); PG8_BAR; PG8_SCHED;
	s_add_u32 s70, s60, 0x4000
	s_addc_u32 s71, s61, 0
	s_add_i32 s90, s90, s15
	v_lshl_add_u64 v[178:179], s[70:71], 0, v[138:139]
	s_mov_b32 m0, s90
	ds_read_b128 v[186:189], v163 offset:49152
	ds_read_b128 v[190:193], v163 offset:50176
	ds_read_b128 v[194:197], v163 offset:51200
	ds_read_b128 v[198:201], v163 offset:52224
	ds_read_b128 v[202:205], v163 offset:53248
	ds_read_b128 v[206:209], v163 offset:54272
	ds_read_b128 v[210:213], v163 offset:55296
	ds_read_b128 v[214:217], v163 offset:56320
	global_load_lds_dwordx4 v[178:179], off
	s_add_i32 m0, s90, 0x2000
	s_add_u32 s60, s60, 0x84000
	v_lshl_add_u64 v[178:179], s[70:71], 0, v[140:141]
	s_addc_u32 s61, s61, 0
	s_add_i32 s70, s91, s15
	global_load_lds_dwordx4 v[178:179], off
	v_lshl_add_u64 v[178:179], s[60:61], 0, v[138:139]
	s_mov_b32 m0, s70
	s_nop 0
	global_load_lds_dwordx4 v[178:179], off
	v_lshl_add_u64 v[178:179], s[60:61], 0, v[140:141]
	s_add_i32 m0, s70, 0x2000
	s_nop 0
	global_load_lds_dwordx4 v[178:179], off
	v_lshl_add_u64 v[178:179], s[58:59], 0, v[138:139]
	s_mov_b32 m0, s79
	s_nop 0
	global_load_lds_dwordx4 v[178:179], off
	v_lshl_add_u64 v[178:179], s[58:59], 0, v[140:141]
	s_mov_b32 m0, s80
	s_nop 0
	global_load_lds_dwordx4 v[178:179], off
	s_waitcnt vmcnt(8)
	s_waitcnt lgkmcnt(0)
	s_barrier
	s_setprio 1
	s_waitcnt lgkmcnt(0)
	v_mfma_f32_16x16x32_bf16 v[62:65], v[130:133], v[186:189], v[62:65]
	v_mfma_f32_16x16x32_bf16 v[58:61], v[152:155], v[186:189], v[58:61]
	v_mfma_f32_16x16x32_bf16 v[46:49], v[130:133], v[194:197], v[46:49]
	v_mfma_f32_16x16x32_bf16 v[42:45], v[152:155], v[194:197], v[42:45]
	v_mfma_f32_16x16x32_bf16 v[30:33], v[130:133], v[202:205], v[30:33]
	v_mfma_f32_16x16x32_bf16 v[26:29], v[152:155], v[202:205], v[26:29]
	v_mfma_f32_16x16x32_bf16 v[14:17], v[130:133], v[210:213], v[14:17]
	v_mfma_f32_16x16x32_bf16 v[10:13], v[152:155], v[210:213], v[10:13]
	v_mfma_f32_16x16x32_bf16 v[62:65], v[134:137], v[190:193], v[62:65]
	v_mfma_f32_16x16x32_bf16 v[58:61], v[156:159], v[190:193], v[58:61]
	v_mfma_f32_16x16x32_bf16 v[46:49], v[134:137], v[198:201], v[46:49]
	v_mfma_f32_16x16x32_bf16 v[42:45], v[156:159], v[198:201], v[42:45]
	v_mfma_f32_16x16x32_bf16 v[30:33], v[134:137], v[206:209], v[30:33]
	v_mfma_f32_16x16x32_bf16 v[26:29], v[156:159], v[206:209], v[26:29]
	v_mfma_f32_16x16x32_bf16 v[14:17], v[134:137], v[214:217], v[14:17]
	v_mfma_f32_16x16x32_bf16 v[10:13], v[156:159], v[214:217], v[10:13]
	s_setprio 0
	s_setprio 1
	v_mfma_f32_16x16x32_bf16 v[54:57], v[166:169], v[186:189], v[54:57]
	v_mfma_f32_16x16x32_bf16 v[50:53], v[174:177], v[186:189], v[50:53]
	v_mfma_f32_16x16x32_bf16 v[38:41], v[166:169], v[194:197], v[38:41]
	v_mfma_f32_16x16x32_bf16 v[34:37], v[174:177], v[194:197], v[34:37]
	v_mfma_f32_16x16x32_bf16 v[22:25], v[166:169], v[202:205], v[22:25]
	v_mfma_f32_16x16x32_bf16 v[18:21], v[174:177], v[202:205], v[18:21]
	v_mfma_f32_16x16x32_bf16 v[6:9], v[166:169], v[210:213], v[6:9]
	v_mfma_f32_16x16x32_bf16 v[2:5], v[174:177], v[210:213], v[2:5]
	v_mfma_f32_16x16x32_bf16 v[54:57], v[170:173], v[190:193], v[54:57]
	v_mfma_f32_16x16x32_bf16 v[50:53], v[182:185], v[190:193], v[50:53]
	v_mfma_f32_16x16x32_bf16 v[38:41], v[170:173], v[198:201], v[38:41]
	v_mfma_f32_16x16x32_bf16 v[34:37], v[182:185], v[198:201], v[34:37]
	v_mfma_f32_16x16x32_bf16 v[22:25], v[170:173], v[206:209], v[22:25]
	v_mfma_f32_16x16x32_bf16 v[18:21], v[182:185], v[206:209], v[18:21]
	v_mfma_f32_16x16x32_bf16 v[6:9], v[170:173], v[214:217], v[6:9]
	v_mfma_f32_16x16x32_bf16 v[2:5], v[182:185], v[214:217], v[2:5]
	s_setprio 0
	s_barrier
	s_add_i32 s89, s89, 2
	s_add_u32 s56, s56, 0x8000
	s_addc_u32 s57, s57, 0
	s_add_u32 s87, s87, 0x8000
	s_addc_u32 s88, s88, 0
	.p2align 6
